# gla_out: the four row sums per iteration as DPP reductions instead of ds_bpermute chains
# speedup vs baseline: 1.0048x; 1.0048x over previous
; __device__ __forceinline__ void gla_out_phase(int wv, const Args& A, int G) {
;     ...
;         for (int u = 0; u < 2; ++u) { const int row = row0 + u; const size_t tok = (size_t)(row >> 2); const int h = row & 3;
;             o4[u] = __builtin_bit_cast(h16x4, *(const u32x2*)(MIX + tok * DM + 1024 + h * 256 + lane * 4));
;             gr[u] = __builtin_bit_cast(h16x4, *(const u32x2*)(PROJ + tok * PW + C_GR + h * 256 + lane * 4));
;             gn[u] = *(const f32x4*)(A.in[18] + h * 256 + lane * 4); }
; #pragma unroll
;         for (int u = 0; u < 2; ++u) { const int row = row0 + u; const size_t tok = (size_t)(row >> 2); const int h = row & 3;
;             float x[4]; float s = 0.f;
; #pragma unroll
;             for (int r = 0; r < 4; ++r) { x[r] = (float)o4[u][r]; s += x[r]; }
;             const float mean = wave_sum(s) * (1.f / 256.f); float q = 0.f;
; #pragma unroll
;             for (int r = 0; r < 4; ++r) { x[r] -= mean; q += x[r] * x[r]; }
;             const float rstd = 1.f / sqrtf(wave_sum(q) * (1.f / 256.f) + LN_EPS); h16x4 y;
.LBB0_2122:
	v_ashrrev_i32_e32 v6, 2, v8
	v_ashrrev_i32_e32 v7, 31, v6
	v_lshlrev_b64 v[12:13], 12, v[6:7]
	v_and_b32_e32 v16, 0x200, v9
	v_lshl_add_u64 v[12:13], s[44:45], 0, v[12:13]
	v_add_u32_e32 v8, s0, v8
	v_lshlrev_b32_e32 v0, 1, v16
	v_lshl_add_u64 v[14:15], v[12:13], 0, v[4:5]
	v_cmp_lt_i32_e32 vcc, s19, v8
	v_mad_i64_i32 v[6:7], s[6:7], v6, s3, v[12:13]
	v_lshl_add_u64 v[12:13], v[14:15], 0, v[0:1]
	s_or_b64 s[12:13], vcc, s[12:13]
	v_add_co_u32_e32 v22, vcc, s4, v12
	v_lshl_add_u64 v[6:7], v[6:7], 0, v[4:5]
	s_nop 0
	v_addc_co_u32_e32 v23, vcc, 0, v13, vcc
	v_lshl_add_u64 v[6:7], v[6:7], 0, v[0:1]
	v_lshlrev_b32_e32 v0, 2, v16
	global_load_dwordx2 v[28:29], v[22:23], off offset:2048
	v_lshl_add_u64 v[24:25], v[6:7], 0, s[16:17]
	v_add_co_u32_e32 v6, vcc, s5, v6
	v_lshl_add_u64 v[26:27], v[2:3], 0, v[0:1]
	v_lshl_add_u64 v[20:21], v[12:13], 0, s[14:15]
	v_addc_co_u32_e32 v7, vcc, 0, v7, vcc
	global_load_dwordx4 v[12:15], v[26:27], off
	global_load_dwordx4 v[16:19], v[26:27], off offset:1024
	global_load_dwordx2 v[30:31], v[6:7], off offset:1536
	global_load_dwordx2 v[32:33], v[24:25], off offset:512
	global_load_dwordx2 v[34:35], v[20:21], off offset:512
	v_add_u32_e32 v9, s1, v9
	s_waitcnt vmcnt(5)
	v_cvt_f32_f16_e32 v6, v28
	v_cvt_f32_f16_sdwa v7, v28 dst_sel:DWORD dst_unused:UNUSED_PAD src0_sel:WORD_1
	v_cvt_f32_f16_e32 v24, v29
	v_cvt_f32_f16_sdwa v25, v29 dst_sel:DWORD dst_unused:UNUSED_PAD src0_sel:WORD_1
	v_add_f32_e32 v0, 0, v6
	v_add_f32_e32 v0, v0, v7
	s_waitcnt vmcnt(2)
	v_cvt_f32_f16_e32 v26, v30
	v_cvt_f32_f16_sdwa v27, v30 dst_sel:DWORD dst_unused:UNUSED_PAD src0_sel:WORD_1
	s_waitcnt vmcnt(0)
	v_cvt_f32_f16_e32 v30, v34
	v_cvt_f32_f16_e32 v28, v31
	v_cvt_f32_f16_sdwa v29, v31 dst_sel:DWORD dst_unused:UNUSED_PAD src0_sel:WORD_1
	v_cvt_f32_f16_sdwa v31, v34 dst_sel:DWORD dst_unused:UNUSED_PAD src0_sel:WORD_1
	v_cvt_f32_f16_e32 v34, v35
	v_cvt_f32_f16_e32 v36, v32
	v_cvt_f32_f16_sdwa v37, v32 dst_sel:DWORD dst_unused:UNUSED_PAD src0_sel:WORD_1
	v_cvt_f32_f16_sdwa v35, v35 dst_sel:DWORD dst_unused:UNUSED_PAD src0_sel:WORD_1
	v_cvt_f32_f16_e32 v32, v33
	v_cvt_f32_f16_sdwa v33, v33 dst_sel:DWORD dst_unused:UNUSED_PAD src0_sel:WORD_1
	v_mul_f32_e32 v38, 0xbfb8aa3b, v26
	v_mul_f32_e32 v39, 0xbfb8aa3b, v27
	v_add_f32_e32 v42, 0, v30
	v_add_f32_e32 v0, v0, v24
	v_exp_f32_e32 v38, v38
	v_exp_f32_e32 v39, v39
	v_add_f32_e32 v42, v42, v31
	v_add_f32_e32 v0, v0, v25
	v_add_f32_e32 v42, v42, v34
	v_mov_b32_e32 v177, v0
	v_mul_f32_e32 v43, 0xbfb8aa3b, v36
	v_mul_f32_e32 v44, 0xbfb8aa3b, v37
	v_mul_f32_e32 v45, 0xbfb8aa3b, v32
	v_mul_f32_e32 v46, 0xbfb8aa3b, v33
	v_add_f32_e32 v48, v42, v35
	v_exp_f32_e32 v43, v43
	v_exp_f32_e32 v44, v44
	v_exp_f32_e32 v45, v45
	v_exp_f32_e32 v46, v46
	v_mov_b32_e32 v178, v48
	v_add_f32_e32 v38, 1.0, v38
	v_add_f32_e32 v39, 1.0, v39
	v_mul_f32_e32 v40, 0xbfb8aa3b, v28
	v_mul_f32_e32 v41, 0xbfb8aa3b, v29
	v_rcp_f32_e32 v38, v38
	v_rcp_f32_e32 v39, v39
	v_exp_f32_e32 v40, v40
	v_exp_f32_e32 v41, v41
	v_add_f32_e32 v42, 1.0, v43
	v_add_f32_e32 v43, 1.0, v44
	v_add_f32_e32 v44, 1.0, v45
	v_add_f32_e32 v45, 1.0, v46
	v_pk_mul_f32 v[26:27], v[38:39], v[26:27]
	v_add_f32_e32 v40, 1.0, v40
	v_add_f32_e32 v41, 1.0, v41
	v_rcp_f32_e32 v40, v40
	v_rcp_f32_e32 v41, v41
	s_nop 0
	v_pk_mul_f32 v[28:29], v[40:41], v[28:29]
	v_rcp_f32_e32 v42, v42
	v_rcp_f32_e32 v43, v43
	v_rcp_f32_e32 v44, v44
	v_pk_mul_f32 v[36:37], v[42:43], v[36:37]
	v_rcp_f32_e32 v45, v45
	s_nop 0
	v_pk_mul_f32 v[32:33], v[44:45], v[32:33]
	s_nop 1
	v_add_f32_dpp v177, v177, v177 row_shr:1 row_mask:0xf bank_mask:0xf
	s_nop 1
	v_add_f32_dpp v177, v177, v177 row_shr:2 row_mask:0xf bank_mask:0xf
	s_nop 1
	v_add_f32_dpp v177, v177, v177 row_shr:4 row_mask:0xf bank_mask:0xf
	s_nop 1
	v_add_f32_dpp v177, v177, v177 row_shr:8 row_mask:0xf bank_mask:0xf
	s_nop 1
	v_add_f32_dpp v177, v177, v177 row_bcast:15 row_mask:0xa bank_mask:0xf
	s_nop 1
	v_add_f32_dpp v177, v177, v177 row_bcast:31 row_mask:0xc bank_mask:0xf
	s_nop 0
	v_readlane_b32 s32, v177, 63
	s_nop 1
	v_mov_b32_e32 v0, s32
	v_mul_f32_e32 v0, 0x3b800000, v0
	v_pk_add_f32 v[6:7], v[6:7], v[0:1] op_sel_hi:[1,0] neg_lo:[0,1] neg_hi:[0,1]
	s_nop 1
	v_add_f32_dpp v178, v178, v178 row_shr:1 row_mask:0xf bank_mask:0xf
	s_nop 1
	v_add_f32_dpp v178, v178, v178 row_shr:2 row_mask:0xf bank_mask:0xf
	s_nop 1
	v_add_f32_dpp v178, v178, v178 row_shr:4 row_mask:0xf bank_mask:0xf
	s_nop 1
	v_add_f32_dpp v178, v178, v178 row_shr:8 row_mask:0xf bank_mask:0xf
	s_nop 1
	v_add_f32_dpp v178, v178, v178 row_bcast:15 row_mask:0xa bank_mask:0xf
	s_nop 1
	v_add_f32_dpp v178, v178, v178 row_bcast:31 row_mask:0xc bank_mask:0xf
	s_nop 0
; __device__ __forceinline__ void gla_out_phase(int wv, const Args& A, int G) {
;     ...
;             const float mean = wave_sum(s) * (1.f / 256.f); float q = 0.f;
; #pragma unroll
;             for (int r = 0; r < 4; ++r) { x[r] -= mean; q += x[r] * x[r]; }
;             const float rstd = 1.f / sqrtf(wave_sum(q) * (1.f / 256.f) + LN_EPS); h16x4 y;
; #pragma unroll
;             for (int r = 0; r < 4; ++r) { const float g = (float)gr[u][r]; y[r] = (h16)(x[r] * rstd * gn[u][r] * (g * __builtin_amdgcn_rcpf(1.f + __expf(-g)))); }
;             *(u32x2*)(MIX + tok * DM + 1024 + h * 256 + lane * 4) = __builtin_bit_cast(u32x2, y); }
	v_readlane_b32 s32, v178, 63
	s_nop 1
	v_mov_b32_e32 v38, s32
	v_pk_add_f32 v[24:25], v[24:25], v[0:1] op_sel_hi:[1,0] neg_lo:[0,1] neg_hi:[0,1]
	v_mul_f32_e32 v0, 0x3b800000, v38
	v_pk_mul_f32 v[38:39], v[6:7], v[6:7]
	v_pk_mul_f32 v[40:41], v[24:25], v[24:25]
	v_pk_add_f32 v[30:31], v[30:31], v[0:1] op_sel_hi:[1,0] neg_lo:[0,1] neg_hi:[0,1]
	v_pk_add_f32 v[34:35], v[34:35], v[0:1] op_sel_hi:[1,0] neg_lo:[0,1] neg_hi:[0,1]
	v_add_f32_e32 v0, v38, v39
	v_pk_mul_f32 v[38:39], v[30:31], v[30:31]
	v_add_f32_e32 v0, v40, v0
	v_pk_mul_f32 v[42:43], v[34:35], v[34:35]
	v_add_f32_e32 v38, v38, v39
	v_add_f32_e32 v0, v41, v0
	v_add_f32_e32 v38, v42, v38
	v_mov_b32_e32 v179, v0
	v_add_f32_e32 v38, v43, v38
	v_mov_b32_e32 v180, v38
	s_nop 1
	v_add_f32_dpp v179, v179, v179 row_shr:1 row_mask:0xf bank_mask:0xf
	s_nop 1
	v_add_f32_dpp v179, v179, v179 row_shr:2 row_mask:0xf bank_mask:0xf
	s_nop 1
	v_add_f32_dpp v179, v179, v179 row_shr:4 row_mask:0xf bank_mask:0xf
	s_nop 1
	v_add_f32_dpp v179, v179, v179 row_shr:8 row_mask:0xf bank_mask:0xf
	s_nop 1
	v_add_f32_dpp v179, v179, v179 row_bcast:15 row_mask:0xa bank_mask:0xf
	s_nop 1
	v_add_f32_dpp v179, v179, v179 row_bcast:31 row_mask:0xc bank_mask:0xf
	s_nop 0
	v_readlane_b32 s32, v179, 63
	s_nop 1
	v_mov_b32_e32 v0, s32
	v_fmamk_f32 v0, v0, 0x3b800000, v10
	s_nop 1
	v_add_f32_dpp v180, v180, v180 row_shr:1 row_mask:0xf bank_mask:0xf
	s_nop 1
	v_add_f32_dpp v180, v180, v180 row_shr:2 row_mask:0xf bank_mask:0xf
	s_nop 1
	v_add_f32_dpp v180, v180, v180 row_shr:4 row_mask:0xf bank_mask:0xf
	s_nop 1
	v_add_f32_dpp v180, v180, v180 row_shr:8 row_mask:0xf bank_mask:0xf
	s_nop 1
	v_add_f32_dpp v180, v180, v180 row_bcast:15 row_mask:0xa bank_mask:0xf
	s_nop 1
	v_add_f32_dpp v180, v180, v180 row_bcast:31 row_mask:0xc bank_mask:0xf
	s_nop 0
	v_readlane_b32 s32, v180, 63
	s_nop 1
	v_mov_b32_e32 v38, s32
	v_mul_f32_e32 v39, 0x4f800000, v0
	v_cmp_gt_f32_e32 vcc, s18, v0
	v_fmamk_f32 v38, v38, 0x3b800000, v10
	v_cmp_gt_f32_e64 s[6:7], s18, v38
	v_cndmask_b32_e32 v0, v0, v39, vcc
	v_mul_f32_e32 v39, 0x4f800000, v38
	v_sqrt_f32_e32 v40, v0
	v_cndmask_b32_e64 v38, v38, v39, s[6:7]
	v_sqrt_f32_e32 v39, v38
	v_add_u32_e32 v41, -1, v40
	v_add_u32_e32 v42, 1, v40
	v_fma_f32 v43, -v41, v40, v0
	v_fma_f32 v44, -v42, v40, v0
	v_add_u32_e32 v45, -1, v39
	v_cmp_ge_f32_e64 s[8:9], 0, v43
	v_add_u32_e32 v46, 1, v39
	v_fma_f32 v43, -v46, v39, v38
	v_cndmask_b32_e64 v40, v40, v41, s[8:9]
	v_fma_f32 v41, -v45, v39, v38
	v_cmp_lt_f32_e64 s[8:9], 0, v44
	s_nop 1
	v_cndmask_b32_e64 v40, v40, v42, s[8:9]
	v_cmp_ge_f32_e64 s[8:9], 0, v41
	v_mul_f32_e32 v41, 0x37800000, v40
	v_cndmask_b32_e32 v40, v40, v41, vcc
	v_cndmask_b32_e64 v39, v39, v45, s[8:9]
	v_cmp_lt_f32_e64 s[8:9], 0, v43
	v_cmp_class_f32_e32 vcc, v0, v11
	s_nop 0
	v_cndmask_b32_e64 v39, v39, v46, s[8:9]
	v_mul_f32_e32 v41, 0x37800000, v39
	v_cndmask_b32_e32 v0, v40, v0, vcc
	v_cndmask_b32_e64 v39, v39, v41, s[6:7]
	v_cmp_class_f32_e32 vcc, v38, v11
	v_div_scale_f32 v40, s[6:7], v0, v0, 1.0
	s_nop 0
	v_cndmask_b32_e32 v38, v39, v38, vcc
	v_rcp_f32_e32 v39, v40
	v_div_scale_f32 v42, s[8:9], v38, v38, 1.0
	v_rcp_f32_e32 v44, v42
	v_fma_f32 v45, -v40, v39, 1.0
	v_div_scale_f32 v41, s[6:7], 1.0, v0, 1.0
	v_fmac_f32_e32 v39, v45, v39
	v_fma_f32 v45, -v42, v44, 1.0
	v_div_scale_f32 v43, s[8:9], 1.0, v38, 1.0
	v_mul_f32_e32 v46, v41, v39
	v_fmac_f32_e32 v44, v45, v44
	v_fma_f32 v45, -v40, v46, v41
	v_mul_f32_e32 v47, v43, v44
	v_fmac_f32_e32 v46, v45, v39
	v_fma_f32 v45, -v42, v47, v43
	v_fma_f32 v40, -v40, v46, v41
	v_fmac_f32_e32 v47, v45, v44
	s_mov_b64 vcc, s[6:7]
	v_div_fmas_f32 v39, v40, v39, v46
	v_fma_f32 v40, -v42, v47, v43
	s_mov_b64 vcc, s[8:9]
	v_div_fixup_f32 v0, v39, v0, 1.0
	v_div_fmas_f32 v39, v40, v44, v47
	v_pk_mul_f32 v[6:7], v[6:7], v[0:1] op_sel_hi:[1,0]
	v_pk_mul_f32 v[24:25], v[24:25], v[0:1] op_sel_hi:[1,0]
	v_div_fixup_f32 v0, v39, v38, 1.0
	v_pk_mul_f32 v[6:7], v[12:13], v[6:7]
	v_pk_mul_f32 v[12:13], v[14:15], v[24:25]
	v_pk_mul_f32 v[14:15], v[30:31], v[0:1] op_sel_hi:[1,0]
	v_pk_mul_f32 v[24:25], v[34:35], v[0:1] op_sel_hi:[1,0]
	v_pk_mul_f32 v[6:7], v[26:27], v[6:7]
	v_pk_mul_f32 v[12:13], v[28:29], v[12:13]
	v_pk_mul_f32 v[14:15], v[16:17], v[14:15]
	v_pk_mul_f32 v[16:17], v[18:19], v[24:25]
	v_cvt_pk_f16_f32 v6, v6, v7
	v_cvt_pk_f16_f32 v7, v12, v13
	v_pk_mul_f32 v[12:13], v[36:37], v[14:15]
	v_pk_mul_f32 v[14:15], v[32:33], v[16:17]
	global_store_dwordx2 v[22:23], v[6:7], off offset:2048
	v_cvt_pk_f16_f32 v6, v12, v13
	v_cvt_pk_f16_f32 v7, v14, v15
	global_store_dwordx2 v[20:21], v[6:7], off offset:512
	s_andn2_b64 exec, exec, s[12:13]
	s_cbranch_execnz .LBB0_2122
